# v13: copy forwarding extended (104 redundant VGPR copies removed)
# baseline (speedup 1.0000x reference)
; __device__ __forceinline__ int crow(int r, int hi) { return (r & 3) + 8 * (r >> 2) + 4 * hi; }
; __device__ void phase_scan(const Params& p, char* lds) {
;     ...
;         if (mat == 0) {
;           float cc[16];
; #pragma unroll
;           for (int r = 0; r < 16; ++r) cc[r] = -0.6065306597126334f * __builtin_amdgcn_rcpf(1.f + __expf(-(acc[r] + bias)));
; #pragma unroll
;           for (int g = 0; g < 4; ++g) { cc[4 * g + 1] += cc[4 * g]; cc[4 * g + 2] += cc[4 * g + 1]; cc[4 * g + 3] += cc[4 * g + 2]; }
;           float run = 0.f;
; #pragma unroll
;           for (int g = 0; g < 4; ++g) {
;             const float own = cc[4 * g + 3];
;             auto rr2 = __builtin_amdgcn_permlane32_swap(__float_as_uint(own), __float_as_uint(own), false, false);
;             const float both = __uint_as_float(rr2[0]) + __uint_as_float(rr2[1]), partner = both - own;
;             const float off = hi ? run + partner : run;
; #pragma unroll
;             for (int e = 0; e < 4; ++e) Pd[crow(4 * g + e, hi) * 64 + jh * 32 + r32] = __expf(off + cc[4 * g + e]);
;             run += both;
;           }
.LBB0_493:
	v_add_f32_e32 v9, v99, v15
	v_mul_f32_e32 v9, 0xbfb8aa3b, v9
	v_exp_f32_e32 v9, v9
	s_andn2_b64 vcc, exec, s[80:81]
	v_add_f32_e32 v9, 1.0, v9
	v_rcp_f32_e32 v9, v9
	s_cbranch_vccnz .LBB0_495
	v_mul_f32_e64 v0, v0, s74
	v_mul_f32_e64 v1, v1, s75
	v_mul_f32_e64 v2, v2, s74
	v_mul_f32_e64 v3, v3, s75
	v_sub_f32_e32 v1, v0, v1
	v_fmamk_f32 v13, v16, 0xbf1b4598, v1
	v_fmamk_f32 v14, v62, 0xbf1b4598, v13
	v_sub_f32_e32 v3, v2, v3
	v_fmamk_f32 v15, v8, 0xbf1b4598, v3
	v_mov_b32_e32 v8, v14
	v_mov_b32_e32 v62, v14
	s_nop 1
	v_permlane32_swap_b32_e32 v8, v62
	v_add_f32_e32 v8, v8, v62
	v_sub_f32_e32 v62, v8, v14
	v_add_f32_e32 v62, 0, v62
	v_cndmask_b32_e64 v62, v62, 0, s[26:27]
	v_add_f32_e32 v0, v0, v62
	v_add_f32_e32 v1, v1, v62
	v_mul_f32_e32 v0, 0x3fb8aa3b, v0
	v_mul_f32_e32 v1, 0x3fb8aa3b, v1
	v_add_f32_e32 v13, v13, v62
	v_add_f32_e32 v14, v14, v62
	v_exp_f32_e32 v0, v0
	v_exp_f32_e32 v1, v1
	v_mul_f32_e32 v13, 0x3fb8aa3b, v13
	v_mul_f32_e32 v14, 0x3fb8aa3b, v14
	v_exp_f32_e32 v13, v13
	v_exp_f32_e32 v14, v14
	v_fmamk_f32 v16, v63, 0xbf1b4598, v15
	ds_write2st64_b32 v187, v0, v1 offset1:1
	ds_write2st64_b32 v187, v13, v14 offset0:2 offset1:3
	v_add_f32_e32 v0, 0, v8
	v_mov_b32_e32 v1, v16
	v_mov_b32_e32 v8, v16
	s_nop 1
	v_permlane32_swap_b32_e32 v1, v8
	v_add_f32_e32 v8, v1, v8
	v_mul_f32_e64 v6, v6, s74
	v_mul_f32_e64 v7, v7, s75
	v_sub_f32_e32 v1, v8, v16
	v_mul_f32_e64 v4, v4, s74
	v_mul_f32_e64 v5, v5, s75
	v_sub_f32_e32 v7, v6, v7
	v_add_f32_e32 v1, v0, v1
	v_sub_f32_e32 v5, v4, v5
	v_fmamk_f32 v12, v12, 0xbf1b4598, v7
	v_cndmask_b32_e64 v1, v1, v0, s[26:27]
	v_fmamk_f32 v10, v10, 0xbf1b4598, v5
	v_fmamk_f32 v62, v9, 0xbf1b4598, v12
	v_add_f32_e32 v2, v2, v1
	v_add_f32_e32 v3, v3, v1
	v_add_f32_e32 v9, v15, v1
	v_add_f32_e32 v1, v16, v1
	v_fmamk_f32 v11, v11, 0xbf1b4598, v10
	v_mul_f32_e32 v9, 0x3fb8aa3b, v9
	v_mul_f32_e32 v1, 0x3fb8aa3b, v1
	v_exp_f32_e32 v13, v9
	v_exp_f32_e32 v14, v1
	v_mov_b32_e32 v1, v11
	v_mov_b32_e32 v9, v11
	s_nop 1
	v_permlane32_swap_b32_e32 v1, v9
	v_add_f32_e64 v0, v0, v8
	v_add_f32_e64 v1, v1, v9
	v_mul_f32_e32 v2, 0x3fb8aa3b, v2
	v_sub_f32_e32 v8, v1, v11
	v_add_f32_e32 v8, v0, v8
	v_mul_f32_e32 v3, 0x3fb8aa3b, v3
	v_cndmask_b32_e64 v8, v8, v0, s[26:27]
	v_exp_f32_e32 v2, v2
	v_exp_f32_e32 v3, v3
	v_add_f32_e32 v4, v4, v8
	v_add_f32_e32 v5, v5, v8
	v_mul_f32_e32 v4, 0x3fb8aa3b, v4
	v_mul_f32_e32 v5, 0x3fb8aa3b, v5
	v_add_f32_e32 v9, v10, v8
	v_add_f32_e32 v8, v11, v8
	v_exp_f32_e32 v4, v4
	v_exp_f32_e32 v5, v5
	v_mul_f32_e32 v9, 0x3fb8aa3b, v9
	v_mul_f32_e32 v8, 0x3fb8aa3b, v8
	v_exp_f32_e32 v9, v9
	v_exp_f32_e32 v8, v8
	ds_write2st64_b32 v187, v2, v3 offset0:8 offset1:9
	ds_write2st64_b32 v187, v13, v14 offset0:10 offset1:11
	ds_write2st64_b32 v187, v4, v5 offset0:16 offset1:17
	ds_write2st64_b32 v187, v9, v8 offset0:18 offset1:19
	v_mov_b32_e32 v3, v62
	v_mov_b32_e32 v5, v62
	s_nop 1
	v_permlane32_swap_b32_e32 v3, v5
	s_nop 0
	v_mov_b32_e32 v4, v1
	v_add_f32_e64 v0, v0, v4
	v_add_f32_e64 v1, v3, v5
	s_mov_b32 s66, 0
	v_sub_f32_e32 v1, v1, v62
	v_add_f32_e32 v1, v0, v1
	v_cndmask_b32_e64 v0, v1, v0, s[26:27]
	v_add_f32_e32 v1, v6, v0
	v_add_f32_e32 v2, v7, v0
	v_add_f32_e32 v3, v12, v0
	v_add_f32_e32 v0, v62, v0
	v_mul_f32_e32 v1, 0x3fb8aa3b, v1
	v_mul_f32_e32 v2, 0x3fb8aa3b, v2
	v_mul_f32_e32 v0, 0x3fb8aa3b, v0
	v_exp_f32_e32 v1, v1
	v_exp_f32_e32 v2, v2
	v_mul_f32_e32 v3, 0x3fb8aa3b, v3
	v_exp_f32_e32 v9, v0
	v_exp_f32_e32 v3, v3
	ds_write2st64_b32 v187, v1, v2 offset0:24 offset1:25
	ds_write_b32 v187, v3 offset:6656
	s_branch .LBB0_496

; __device__ void phase_scan(const Params& p, char* lds) {
;     ...
;         const float inv = rsqrtf(fmaxf(ss, 1e-24f));
; #pragma unroll
;         for (int e = 0; e < 8; ++e) kk[e] *= inv;
;       };
;       auto stageB = [&](int c) {
;         char* buf = lds + (c & 1) * SC_BUF;
;         const f32x4 i0 = *(const f32x4*)(IC + pstep * 64 + j0), i1 = *(const f32x4*)(IC + pstep * 64 + j0 + 4);
;         const float ic[8] = {i0[0], i0[1], i0[2], i0[3], i1[0], i1[1], i1[2], i1[3]};
;         const float* Pt = (const float*)(buf + SC_P) + pstep * 64 + j0;
;         const f32x4 pt0 = *(const f32x4*)(Pt), pt1 = *(const f32x4*)(Pt + 4);
;         f32x4 pm0 = {1.f, 1.f, 1.f, 1.f}, pm1 = pm0;
;         if (pstep > 0) { pm0 = *(const f32x4*)(Pt - 64); pm1 = *(const f32x4*)(Pt - 60); }
;         const float pt[8] = {pt0[0], pt0[1], pt0[2], pt0[3], pt1[0], pt1[1], pt1[2], pt1[3]};
;         const float pm[8] = {pm0[0], pm0[1], pm0[2], pm0[3], pm1[0], pm1[1], pm1[2], pm1[3]};
;         const u32x4 an = {cvtpk(-kk[0] * pm[0], -kk[1] * pm[1]), cvtpk(-kk[2] * pm[2], -kk[3] * pm[3]), cvtpk(-kk[4] * pm[4], -kk[5] * pm[5]), cvtpk(-kk[6] * pm[6], -kk[7] * pm[7])};
;         const u32x4 rn = {cvtpk(rr[0] * pt[0], rr[1] * pt[1]), cvtpk(rr[2] * pt[2], rr[3] * pt[3]), cvtpk(rr[4] * pt[4], rr[5] * pt[5]), cvtpk(rr[6] * pt[6], rr[7] * pt[7])};
;         bf16_t* ARa = (bf16_t*)(buf + SC_ARA) + (pblk * 4 + psb) * 64; bf16_t* ARr = (bf16_t*)(buf + SC_ARR) + (pblk * 4 + psb) * 64;
;         { u32x2 lo = {an[0], an[1]}, hi2 = {an[2], an[3]}; *(u32x2*)(ARa + apos0) = lo; *(u32x2*)(ARa + apos1) = hi2; }
;         { u32x2 lo = {rn[0], rn[1]}, hi2 = {rn[2], rn[3]}; *(u32x2*)(ARr + apos0) = lo; *(u32x2*)(ARr + apos1) = hi2; }
;         *(u32x4*)(SCR + (pstep * 4 + 0) * 64 + j0) = an; *(u32x4*)(SCR + (pstep * 4 + 1) * 64 + j0) = rn;
;         float bs = 0.f;
;         unsigned bq[8], kq[8];
;         unsigned* BK = (unsigned*)(buf + SC_BK) + (pblk * 64 + j0) * 4 + psb;
; #pragma unroll
;         for (int e = 0; e < 8; ++e) {
;           const float kd = kr[e] * (1.f + (ic[e] - 1.f) * kac[e]);
;           const float ip = __builtin_amdgcn_rcpf(pt[e]);
;           const unsigned pr2 = cvtpk(kk[e] * ic[e] * ip, kd * ip);
;           BK[e * 4] = pr2;
;           bq[e] = pr2 & 0xffffu; kq[e] = pr2 >> 16;
;           bs += rr[e] * kd * rkc[e];
;         }
.LBB0_498:
	s_or_b64 exec, exec, s[80:81]
	v_add_f32_e32 v101, v101, v120
	v_max_f32_e32 v101, 0x179abe15, v101
	v_rsq_f32_e32 v120, v101
	v_lshlrev_b32_e32 v122, 16, v58
	v_and_b32_e32 v123, 0xffff0000, v58
	v_lshlrev_b32_e32 v124, 16, v59
	v_mul_f32_e64 v112, v112, v120
	v_mul_f32_e64 v113, v113, v120
	v_mul_f32_e64 v114, v114, v120
	v_mul_f32_e64 v115, v115, v120
	v_and_b32_e32 v125, 0xffff0000, v59
	v_lshlrev_b32_e32 v126, 16, v60
	v_and_b32_e32 v127, 0xffff0000, v60
	v_lshlrev_b32_e32 v128, 16, v61
	v_and_b32_e32 v129, 0xffff0000, v61
	v_mul_f32_e64 v116, v116, v120
	v_mul_f32_e64 v117, v117, v120
	v_mul_f32_e64 v118, v118, v120
	v_mul_f32_e64 v119, v119, v120
	s_waitcnt lgkmcnt(1)
	v_mul_f32_e64 v58, v82, -v112
	v_mul_f32_e64 v59, v83, -v113
	v_mul_f32_e64 v60, v84, -v114
	v_mul_f32_e64 v61, v85, -v115
	v_cvt_pk_bf16_f32 v58, v58, v59
	v_cvt_pk_bf16_f32 v59, v60, v61
	s_waitcnt lgkmcnt(0)
	v_mul_f32_e64 v60, v78, -v116
	v_mul_f32_e64 v61, v79, -v117
	v_mul_f32_e64 v78, v80, -v118
	v_mul_f32_e64 v79, v81, -v119
	v_cvt_pk_bf16_f32 v60, v60, v61
	v_cvt_pk_bf16_f32 v61, v78, v79
	v_mul_f32_e64 v78, v74, v122
	v_mul_f32_e64 v79, v75, v123
	v_mul_f32_e64 v80, v76, v124
	v_mul_f32_e64 v81, v77, v125
	v_cvt_pk_bf16_f32 v78, v78, v79
	v_cvt_pk_bf16_f32 v79, v80, v81
	v_mul_f32_e64 v80, v8, v126
	v_mul_f32_e64 v81, v9, v127
	v_mul_f32_e64 v82, v10, v128
	v_mul_f32_e64 v83, v11, v129
	v_cvt_pk_bf16_f32 v80, v80, v81
	v_cvt_pk_bf16_f32 v81, v82, v83
	v_add_u32_e32 v82, 0x2000, v194
	ds_write2_b64 v82, v[58:59], v[60:61] offset1:2
	v_add_u32_e32 v82, 0x3000, v194
	ds_write2_b64 v82, v[78:79], v[80:81] offset1:2
	ds_write_b128 v195, v[58:61]
	ds_write_b128 v195, v[78:81] offset:128
	v_add_f32_e32 v58, -1.0, v12
	v_fma_f32 v59, v22, v58, 1.0
	v_rcp_f32_e32 v60, v74
	s_nop 0
	s_nop 0
	s_nop 0
	v_mul_f32_e64 v58, v12, v112
	v_mul_f32_e64 v59, v59, v110
	v_mov_b32_e32 v110, v113
	v_mul_f32_e32 v12, v59, v122
	v_fma_f32 v79, v30, v12, 0
	v_add_f32_e32 v12, -1.0, v13
	v_mul_f32_e64 v61, v59, v60
	v_mul_f32_e64 v60, v58, v60
	v_fma_f32 v59, v23, v12, 1.0
	v_rcp_f32_e32 v12, v75
	s_nop 0
	v_mul_f32_e64 v58, v13, v110
	v_mul_f32_e64 v59, v59, v111
	v_cvt_pk_bf16_f32 v60, v60, v61
	v_mul_f32_e64 v13, v59, v12
	v_mul_f32_e64 v12, v58, v12
	v_rcp_f32_e32 v58, v76
	v_cvt_pk_bf16_f32 v75, v12, v13
	v_mul_f32_e32 v12, v59, v123
	v_add_u32_e32 v80, 0x4000, v198
	v_fmac_f32_e32 v79, v31, v12
	v_add_f32_e32 v12, -1.0, v14
	v_and_b32_e32 v74, 0xffff, v60
	v_lshrrev_b32_e32 v78, 16, v60
	ds_write2_b32 v80, v60, v75 offset1:4
	v_fma_f32 v13, v24, v12, 1.0
	s_nop 0
	s_nop 0
	s_nop 0
	v_mul_f32_e64 v12, v14, v114
	v_mul_f32_e64 v13, v13, v108
	v_rcp_f32_e32 v14, v77
	v_mul_f32_e64 v59, v13, v58
	v_mul_f32_e64 v58, v12, v58
	v_mul_f32_e32 v12, v13, v124
	v_fmac_f32_e32 v79, v32, v12
	v_add_f32_e32 v12, -1.0, v15
	v_fma_f32 v13, v25, v12, 1.0
	s_nop 0
	v_mov_b32_e32 v108, v115
	v_mul_f32_e64 v12, v15, v108
	v_mul_f32_e64 v13, v13, v109
	v_rcp_f32_e32 v8, v8
	v_mul_f32_e64 v15, v13, v14
	v_mul_f32_e64 v14, v12, v14
	v_mul_f32_e32 v12, v13, v125
	v_fmac_f32_e32 v79, v33, v12
	v_add_f32_e32 v12, -1.0, v4
	v_cvt_pk_bf16_f32 v61, v14, v15
	v_fma_f32 v13, v18, v12, 1.0
	s_nop 0
	s_nop 0
	s_nop 0
	v_mul_f32_e64 v12, v116, v4
	v_mul_f32_e64 v13, v13, v106
	v_mov_b32_e32 v106, v5
	v_mul_f32_e32 v4, v13, v126
	v_fmac_f32_e32 v79, v26, v4
	v_add_f32_e32 v4, -1.0, v5
	v_mul_f32_e64 v14, v12, v8
	v_mul_f32_e64 v15, v13, v8
	v_fma_f32 v13, v19, v4, 1.0
	v_rcp_f32_e32 v4, v9
	s_nop 0
	v_mul_f32_e64 v8, v117, v106
	v_mul_f32_e64 v9, v13, v107
	s_nop 0
	v_mul_f32_e64 v5, v9, v4
	v_mul_f32_e64 v4, v8, v4
	v_rcp_f32_e32 v8, v10
	v_cvt_pk_bf16_f32 v76, v4, v5
	v_mul_f32_e32 v4, v9, v127
	v_fmac_f32_e32 v79, v27, v4
	v_add_f32_e32 v4, -1.0, v6
	v_fma_f32 v5, v20, v4, 1.0
	s_nop 0
	v_mov_b32_e32 v13, v104
	v_mul_f32_e64 v4, v118, v6
	v_mul_f32_e64 v5, v5, v13
	v_rcp_f32_e32 v6, v11
	v_mul_f32_e64 v9, v5, v8
	v_mul_f32_e64 v8, v4, v8
	v_mul_f32_e32 v4, v5, v128
	v_fmac_f32_e32 v79, v28, v4
	v_add_f32_e32 v4, -1.0, v7
	v_fma_f32 v5, v21, v4, 1.0
	s_nop 0
	v_mov_b32_e32 v104, v7
	v_mul_f32_e64 v4, v119, v104
	v_mul_f32_e64 v5, v5, v105
	v_cvt_pk_bf16_f32 v58, v58, v59
	v_cvt_pk_bf16_f32 v14, v14, v15
	v_cvt_pk_bf16_f32 v8, v8, v9
	v_mul_f32_e64 v7, v5, v6
	v_mul_f32_e64 v6, v4, v6
	v_and_b32_e32 v59, 0xffff, v58
	v_and_b32_e32 v15, 0xffff, v14
	v_and_b32_e32 v9, 0xffff, v8
	v_cvt_pk_bf16_f32 v11, v6, v7
	v_mul_f32_e32 v4, v5, v129
	v_lshrrev_b32_e32 v60, 16, v58
	ds_write2_b32 v80, v58, v61 offset0:8 offset1:12
	v_lshrrev_b32_e32 v58, 16, v14
	v_lshrrev_b32_e32 v12, 16, v8
	v_fmac_f32_e32 v79, v29, v4
	v_lshl_or_b32 v4, v75, 16, v74
	v_lshl_or_b32 v5, v61, 16, v59
	v_lshl_or_b32 v6, v76, 16, v15
	v_lshl_or_b32 v7, v11, 16, v9
	s_mul_i32 s73, s76, 0x420000
	ds_write2_b32 v80, v14, v76 offset0:16 offset1:20
	ds_write2_b32 v80, v8, v11 offset0:24 offset1:28
	v_and_or_b32 v8, v75, s1, v78
	v_and_or_b32 v9, v61, s1, v60
	v_and_or_b32 v10, v76, s1, v58
	v_and_or_b32 v11, v11, s1, v12
	ds_write_b128 v195, v[4:7] offset:256
	ds_write_b128 v195, v[8:11] offset:384
	v_add_f32_dpp v4, v79, v79 quad_perm:[1,0,3,2] row_mask:0xf bank_mask:0xf bound_ctrl:1
	s_mul_hi_i32 s66, s76, 0x420000
	s_add_u32 s76, s43, s73
	v_add_f32_dpp v4, v4, v4 quad_perm:[2,3,0,1] row_mask:0xf bank_mask:0xf bound_ctrl:1
	s_addc_u32 s77, s95, s66
	s_nop 0
	v_mov_b32_dpp v5, v4 row_half_mirror row_mask:0xf bank_mask:0xf bound_ctrl:1
	s_and_saveexec_b64 s[80:81], s[8:9]
	s_cbranch_execz .LBB0_500
	v_lshlrev_b64 v[6:7], 6, v[102:103]
	v_lshl_add_u64 v[6:7], s[76:77], 0, v[6:7]
	s_lshl_b32 s66, s31, 2
	v_lshl_add_u64 v[6:7], v[6:7], 0, s[66:67]
	v_add_f32_e32 v4, v4, v5
	global_store_dword v[6:7], v4, off

; __device__ __forceinline__ int crow(int r, int hi) { return (r & 3) + 8 * (r >> 2) + 4 * hi; }
; __device__ void phase_scan(const Params& p, char* lds) {
;     ...
;         if (mat == 0) {
;           float cc[16];
; #pragma unroll
;           for (int r = 0; r < 16; ++r) cc[r] = -0.6065306597126334f * __builtin_amdgcn_rcpf(1.f + __expf(-(acc[r] + bias)));
; #pragma unroll
;           for (int g = 0; g < 4; ++g) { cc[4 * g + 1] += cc[4 * g]; cc[4 * g + 2] += cc[4 * g + 1]; cc[4 * g + 3] += cc[4 * g + 2]; }
;           float run = 0.f;
; #pragma unroll
;           for (int g = 0; g < 4; ++g) {
;             const float own = cc[4 * g + 3];
;             auto rr2 = __builtin_amdgcn_permlane32_swap(__float_as_uint(own), __float_as_uint(own), false, false);
;             const float both = __uint_as_float(rr2[0]) + __uint_as_float(rr2[1]), partner = both - own;
;             const float off = hi ? run + partner : run;
; #pragma unroll
;             for (int e = 0; e < 4; ++e) Pd[crow(4 * g + e, hi) * 64 + jh * 32 + r32] = __expf(off + cc[4 * g + e]);
;             run += both;
;           }
.LBB0_518:
	v_add_f32_e32 v8, v99, v15
	v_mul_f32_e32 v8, 0xbfb8aa3b, v8
	v_exp_f32_e32 v8, v8
	s_andn2_b64 vcc, exec, s[80:81]
	v_add_f32_e32 v8, 1.0, v8
	v_rcp_f32_e32 v8, v8
	s_cbranch_vccnz .LBB0_520
	v_mul_f32_e64 v0, v0, s74
	v_mul_f32_e64 v1, v1, s75
	v_mul_f32_e64 v2, v2, s74
	v_mul_f32_e64 v3, v3, s75
	v_sub_f32_e32 v1, v0, v1
	v_fmamk_f32 v12, v58, 0xbf1b4598, v1
	v_fmamk_f32 v13, v59, 0xbf1b4598, v12
	v_mov_b32_e32 v58, v13
	v_mov_b32_e32 v59, v13
	s_nop 1
	v_permlane32_swap_b32_e32 v58, v59
	v_add_f32_e32 v58, v58, v59
	v_sub_f32_e32 v59, v58, v13
	v_add_f32_e32 v59, 0, v59
	v_cndmask_b32_e64 v59, v59, 0, s[26:27]
	v_add_f32_e32 v0, v0, v59
	v_add_f32_e32 v1, v1, v59
	v_mul_f32_e32 v0, 0x3fb8aa3b, v0
	v_mul_f32_e32 v1, 0x3fb8aa3b, v1
	v_add_f32_e32 v12, v12, v59
	v_add_f32_e32 v13, v13, v59
	v_exp_f32_e32 v0, v0
	v_exp_f32_e32 v1, v1
	v_mul_f32_e32 v12, 0x3fb8aa3b, v12
	v_mul_f32_e32 v13, 0x3fb8aa3b, v13
	v_mul_f32_e64 v6, v6, s74
	v_mul_f32_e64 v7, v7, s75
	v_sub_f32_e32 v3, v2, v3
	v_exp_f32_e32 v12, v12
	v_exp_f32_e32 v13, v13
	v_fmamk_f32 v14, v60, 0xbf1b4598, v3
	v_sub_f32_e32 v7, v6, v7
	v_fmamk_f32 v15, v61, 0xbf1b4598, v14
	v_fmamk_f32 v59, v9, 0xbf1b4598, v7
	v_fmamk_f32 v60, v8, 0xbf1b4598, v59
	ds_write2st64_b32 v187, v0, v1 offset0:132 offset1:133
	ds_write2st64_b32 v187, v12, v13 offset0:134 offset1:135
	v_mov_b32_e32 v1, v15
	v_mov_b32_e32 v8, v15
	s_nop 1
	v_permlane32_swap_b32_e32 v1, v8
	v_add_f32_e32 v8, v1, v8
	v_add_f32_e32 v0, 0, v58
	v_sub_f32_e32 v1, v8, v15
	v_mul_f32_e64 v4, v4, s74
	v_mul_f32_e64 v5, v5, s75
	v_add_f32_e32 v1, v0, v1
	v_sub_f32_e32 v5, v4, v5
	v_cndmask_b32_e64 v1, v1, v0, s[26:27]
	v_fmamk_f32 v10, v10, 0xbf1b4598, v5
	v_add_f32_e32 v2, v2, v1
	v_add_f32_e32 v3, v3, v1
	v_add_f32_e32 v9, v14, v1
	v_add_f32_e32 v1, v15, v1
	v_fmamk_f32 v11, v11, 0xbf1b4598, v10
	v_mul_f32_e32 v9, 0x3fb8aa3b, v9
	v_mul_f32_e32 v1, 0x3fb8aa3b, v1
	v_exp_f32_e32 v12, v9
	v_exp_f32_e32 v13, v1
	v_mov_b32_e32 v1, v11
	v_mov_b32_e32 v9, v11
	s_nop 1
	v_permlane32_swap_b32_e32 v1, v9
	v_add_f32_e64 v0, v0, v8
	v_add_f32_e64 v1, v1, v9
	v_mul_f32_e32 v2, 0x3fb8aa3b, v2
	v_sub_f32_e32 v8, v1, v11
	v_add_f32_e32 v8, v0, v8
	v_mul_f32_e32 v3, 0x3fb8aa3b, v3
	v_cndmask_b32_e64 v8, v8, v0, s[26:27]
	v_exp_f32_e32 v2, v2
	v_exp_f32_e32 v3, v3
	v_add_f32_e32 v4, v4, v8
	v_add_f32_e32 v5, v5, v8
	v_mul_f32_e32 v4, 0x3fb8aa3b, v4
	v_mul_f32_e32 v5, 0x3fb8aa3b, v5
	v_add_f32_e32 v9, v10, v8
	v_add_f32_e32 v8, v11, v8
	v_exp_f32_e32 v4, v4
	v_exp_f32_e32 v5, v5
	v_mul_f32_e32 v9, 0x3fb8aa3b, v9
	v_mul_f32_e32 v8, 0x3fb8aa3b, v8
	v_exp_f32_e32 v9, v9
	v_exp_f32_e32 v8, v8
	ds_write2st64_b32 v187, v2, v3 offset0:140 offset1:141
	ds_write2st64_b32 v187, v12, v13 offset0:142 offset1:143
	ds_write2st64_b32 v187, v4, v5 offset0:148 offset1:149
	ds_write2st64_b32 v187, v9, v8 offset0:150 offset1:151
	v_mov_b32_e32 v3, v60
	v_mov_b32_e32 v5, v60
	s_nop 1
	v_permlane32_swap_b32_e32 v3, v5
	s_nop 0
	v_mov_b32_e32 v4, v1
	v_add_f32_e64 v0, v0, v4
	v_add_f32_e64 v1, v3, v5
	v_readlane_b32 s66, v255, 15
	v_sub_f32_e32 v1, v1, v60
	v_add_f32_e32 v1, v0, v1
	v_cndmask_b32_e64 v0, v1, v0, s[26:27]
	v_add_f32_e32 v1, v6, v0
	v_add_f32_e32 v2, v7, v0
	v_add_f32_e32 v3, v59, v0
	v_add_f32_e32 v0, v60, v0
	v_mul_f32_e32 v1, 0x3fb8aa3b, v1
	v_mul_f32_e32 v2, 0x3fb8aa3b, v2
	v_mul_f32_e32 v0, 0x3fb8aa3b, v0
	v_exp_f32_e32 v1, v1
	v_exp_f32_e32 v2, v2
	v_mul_f32_e32 v3, 0x3fb8aa3b, v3
	v_exp_f32_e32 v8, v0
	v_exp_f32_e32 v3, v3
	ds_write2st64_b32 v187, v1, v2 offset0:156 offset1:157
	ds_write_b32 v187, v3 offset:40448
	s_branch .LBB0_521

; __device__ void phase_scan(const Params& p, char* lds) {
;     ...
;         const float inv = rsqrtf(fmaxf(ss, 1e-24f));
; #pragma unroll
;         for (int e = 0; e < 8; ++e) kk[e] *= inv;
;       };
;       auto stageB = [&](int c) {
;         char* buf = lds + (c & 1) * SC_BUF;
;         const f32x4 i0 = *(const f32x4*)(IC + pstep * 64 + j0), i1 = *(const f32x4*)(IC + pstep * 64 + j0 + 4);
;         const float ic[8] = {i0[0], i0[1], i0[2], i0[3], i1[0], i1[1], i1[2], i1[3]};
;         const float* Pt = (const float*)(buf + SC_P) + pstep * 64 + j0;
;         const f32x4 pt0 = *(const f32x4*)(Pt), pt1 = *(const f32x4*)(Pt + 4);
;         f32x4 pm0 = {1.f, 1.f, 1.f, 1.f}, pm1 = pm0;
;         if (pstep > 0) { pm0 = *(const f32x4*)(Pt - 64); pm1 = *(const f32x4*)(Pt - 60); }
;         const float pt[8] = {pt0[0], pt0[1], pt0[2], pt0[3], pt1[0], pt1[1], pt1[2], pt1[3]};
;         const float pm[8] = {pm0[0], pm0[1], pm0[2], pm0[3], pm1[0], pm1[1], pm1[2], pm1[3]};
;         const u32x4 an = {cvtpk(-kk[0] * pm[0], -kk[1] * pm[1]), cvtpk(-kk[2] * pm[2], -kk[3] * pm[3]), cvtpk(-kk[4] * pm[4], -kk[5] * pm[5]), cvtpk(-kk[6] * pm[6], -kk[7] * pm[7])};
;         const u32x4 rn = {cvtpk(rr[0] * pt[0], rr[1] * pt[1]), cvtpk(rr[2] * pt[2], rr[3] * pt[3]), cvtpk(rr[4] * pt[4], rr[5] * pt[5]), cvtpk(rr[6] * pt[6], rr[7] * pt[7])};
;         bf16_t* ARa = (bf16_t*)(buf + SC_ARA) + (pblk * 4 + psb) * 64; bf16_t* ARr = (bf16_t*)(buf + SC_ARR) + (pblk * 4 + psb) * 64;
;         { u32x2 lo = {an[0], an[1]}, hi2 = {an[2], an[3]}; *(u32x2*)(ARa + apos0) = lo; *(u32x2*)(ARa + apos1) = hi2; }
;         { u32x2 lo = {rn[0], rn[1]}, hi2 = {rn[2], rn[3]}; *(u32x2*)(ARr + apos0) = lo; *(u32x2*)(ARr + apos1) = hi2; }
;         *(u32x4*)(SCR + (pstep * 4 + 0) * 64 + j0) = an; *(u32x4*)(SCR + (pstep * 4 + 1) * 64 + j0) = rn;
;         float bs = 0.f;
;         unsigned bq[8], kq[8];
;         unsigned* BK = (unsigned*)(buf + SC_BK) + (pblk * 64 + j0) * 4 + psb;
; #pragma unroll
;         for (int e = 0; e < 8; ++e) {
;           const float kd = kr[e] * (1.f + (ic[e] - 1.f) * kac[e]);
;           const float ip = __builtin_amdgcn_rcpf(pt[e]);
;           const unsigned pr2 = cvtpk(kk[e] * ic[e] * ip, kd * ip);
;           BK[e * 4] = pr2;
;           bq[e] = pr2 & 0xffffu; kq[e] = pr2 >> 16;
;           bs += rr[e] * kd * rkc[e];
;         }
.LBB0_523:
	s_or_b64 exec, exec, s[78:79]
	v_add_f32_e32 v101, v101, v118
	v_max_f32_e32 v101, 0x179abe15, v101
	v_rsq_f32_e32 v118, v101
	v_lshlrev_b32_e32 v120, 16, v86
	v_and_b32_e32 v121, 0xffff0000, v86
	v_lshlrev_b32_e32 v122, 16, v87
	v_mul_f32_e64 v110, v110, v118
	v_mul_f32_e64 v111, v111, v118
	v_mul_f32_e64 v112, v112, v118
	v_mul_f32_e64 v113, v113, v118
	v_and_b32_e32 v123, 0xffff0000, v87
	v_lshlrev_b32_e32 v124, 16, v88
	v_and_b32_e32 v125, 0xffff0000, v88
	v_lshlrev_b32_e32 v126, 16, v89
	v_and_b32_e32 v127, 0xffff0000, v89
	v_mul_f32_e64 v114, v114, v118
	v_mul_f32_e64 v115, v115, v118
	v_mul_f32_e64 v116, v116, v118
	v_mul_f32_e64 v117, v117, v118
	s_waitcnt lgkmcnt(1)
	v_mul_f32_e64 v86, v94, -v110
	v_mul_f32_e64 v87, v95, -v111
	v_mul_f32_e64 v88, v96, -v112
	v_mul_f32_e64 v89, v97, -v113
	v_cvt_pk_bf16_f32 v86, v86, v87
	v_cvt_pk_bf16_f32 v87, v88, v89
	s_waitcnt lgkmcnt(0)
	v_mul_f32_e64 v88, v90, -v114
	v_mul_f32_e64 v89, v91, -v115
	v_mul_f32_e64 v90, v92, -v116
	v_mul_f32_e64 v91, v93, -v117
	v_cvt_pk_bf16_f32 v88, v88, v89
	v_cvt_pk_bf16_f32 v89, v90, v91
	v_mul_f32_e64 v90, v12, v120
	v_mul_f32_e64 v91, v13, v121
	v_mul_f32_e64 v92, v14, v122
	v_mul_f32_e64 v93, v15, v123
	v_cvt_pk_bf16_f32 v90, v90, v91
	v_cvt_pk_bf16_f32 v91, v92, v93
	v_mul_f32_e64 v92, v4, v124
	v_mul_f32_e64 v93, v5, v125
	v_mul_f32_e64 v94, v6, v126
	v_mul_f32_e64 v95, v7, v127
	v_cvt_pk_bf16_f32 v92, v92, v93
	v_cvt_pk_bf16_f32 v93, v94, v95
	v_add_u32_e32 v94, 0xa000, v194
	ds_write2_b64 v94, v[86:87], v[88:89] offset0:128 offset1:130
	v_add_u32_e32 v94, 0xb000, v194
	ds_write2_b64 v94, v[90:91], v[92:93] offset0:128 offset1:130
	ds_write_b128 v195, v[86:89]
	ds_write_b128 v195, v[90:93] offset:128
	v_add_f32_e32 v86, -1.0, v8
	v_fma_f32 v87, v22, v86, 1.0
	v_rcp_f32_e32 v12, v12
	s_nop 0
	s_nop 0
	s_nop 0
	v_mul_f32_e64 v86, v110, v8
	v_mul_f32_e64 v87, v87, v108
	v_mov_b32_e32 v108, v9
	v_mul_f32_e32 v8, v87, v120
	v_fma_f32 v91, v30, v8, 0
	v_add_f32_e32 v8, -1.0, v9
	v_mul_f32_e64 v88, v86, v12
	v_mul_f32_e64 v89, v87, v12
	v_fma_f32 v87, v23, v8, 1.0
	v_rcp_f32_e32 v8, v13
	s_nop 0
	v_mul_f32_e64 v12, v111, v108
	v_mul_f32_e64 v13, v87, v109
	s_nop 0
	v_mul_f32_e64 v9, v13, v8
	v_mul_f32_e64 v8, v12, v8
	v_rcp_f32_e32 v12, v14
	v_cvt_pk_bf16_f32 v92, v8, v9
	v_mul_f32_e32 v8, v13, v121
	v_fmac_f32_e32 v91, v31, v8
	v_add_f32_e32 v8, -1.0, v10
	v_fma_f32 v9, v24, v8, 1.0
	s_nop 0
	v_mov_b32_e32 v87, v106
	v_mul_f32_e64 v8, v112, v10
	v_mul_f32_e64 v9, v9, v87
	v_rcp_f32_e32 v10, v15
	v_mul_f32_e64 v13, v9, v12
	v_mul_f32_e64 v12, v8, v12
	v_mul_f32_e32 v8, v9, v122
	v_fmac_f32_e32 v91, v32, v8
	v_add_f32_e32 v8, -1.0, v11
	v_fma_f32 v9, v25, v8, 1.0
	s_nop 0
	v_mov_b32_e32 v106, v11
	v_mul_f32_e64 v8, v113, v106
	v_mul_f32_e64 v9, v9, v107
	v_rcp_f32_e32 v4, v4
	v_mul_f32_e64 v11, v9, v10
	v_mul_f32_e64 v10, v8, v10
	v_mul_f32_e32 v8, v9, v123
	v_fmac_f32_e32 v91, v33, v8
	v_add_f32_e32 v8, -1.0, v0
	v_cvt_pk_bf16_f32 v15, v10, v11
	v_fma_f32 v9, v18, v8, 1.0
	s_nop 0
	s_nop 0
	s_nop 0
	v_mul_f32_e64 v8, v114, v0
	v_mul_f32_e64 v9, v9, v104
	v_mov_b32_e32 v104, v1
	v_mul_f32_e32 v0, v9, v124
	v_fmac_f32_e32 v91, v26, v0
	v_add_f32_e32 v0, -1.0, v1
	v_mul_f32_e64 v10, v8, v4
	v_mul_f32_e64 v11, v9, v4
	v_fma_f32 v9, v19, v0, 1.0
	v_rcp_f32_e32 v0, v5
	s_nop 0
	v_mul_f32_e64 v4, v115, v104
	v_mul_f32_e64 v5, v9, v105
	s_nop 0
	v_mul_f32_e64 v1, v5, v0
	v_mul_f32_e64 v0, v4, v0
	v_rcp_f32_e32 v4, v6
	v_cvt_pk_bf16_f32 v86, v0, v1
	v_mul_f32_e32 v0, v5, v125
	v_fmac_f32_e32 v91, v27, v0
	v_add_f32_e32 v0, -1.0, v2
	v_fma_f32 v1, v20, v0, 1.0
	s_nop 0
	v_mov_b32_e32 v9, v102
	v_mul_f32_e64 v0, v116, v2
	v_mul_f32_e64 v1, v1, v9
	v_rcp_f32_e32 v2, v7
	v_mul_f32_e64 v5, v1, v4
	v_mul_f32_e64 v4, v0, v4
	v_mul_f32_e32 v0, v1, v126
	v_fmac_f32_e32 v91, v28, v0
	v_add_f32_e32 v0, -1.0, v3
	v_fma_f32 v1, v21, v0, 1.0
	s_nop 0
	v_mov_b32_e32 v102, v3
	v_mul_f32_e64 v0, v117, v102
	v_mul_f32_e64 v1, v1, v103
	v_cvt_pk_bf16_f32 v88, v88, v89
	v_cvt_pk_bf16_f32 v12, v12, v13
	v_cvt_pk_bf16_f32 v10, v10, v11
	v_cvt_pk_bf16_f32 v4, v4, v5
	v_mul_f32_e64 v3, v1, v2
	v_mul_f32_e64 v2, v0, v2
	v_and_b32_e32 v89, 0xffff, v88
	v_add_u32_e32 v93, 0xc400, v198
	v_and_b32_e32 v13, 0xffff, v12
	v_and_b32_e32 v11, 0xffff, v10
	v_and_b32_e32 v5, 0xffff, v4
	v_cvt_pk_bf16_f32 v7, v2, v3
	v_mul_f32_e32 v0, v1, v127
	v_lshrrev_b32_e32 v90, 16, v88
	v_lshrrev_b32_e32 v14, 16, v12
	ds_write2_b32 v93, v12, v15 offset0:8 offset1:12
	v_lshrrev_b32_e32 v12, 16, v10
	v_lshrrev_b32_e32 v8, 16, v4
	v_fmac_f32_e32 v91, v29, v0
	v_lshl_or_b32 v0, v92, 16, v89
	v_lshl_or_b32 v1, v15, 16, v13
	v_lshl_or_b32 v2, v86, 16, v11
	v_lshl_or_b32 v3, v7, 16, v5
	s_lshl_b32 s31, s31, 2
	ds_write2_b32 v93, v88, v92 offset1:4
	ds_write2_b32 v93, v10, v86 offset0:16 offset1:20
	ds_write2_b32 v93, v4, v7 offset0:24 offset1:28
	v_and_or_b32 v4, v92, s1, v90
	v_and_or_b32 v5, v15, s1, v14
	v_and_or_b32 v6, v86, s1, v12
	v_and_or_b32 v7, v7, s1, v8
	ds_write_b128 v195, v[0:3] offset:256
	ds_write_b128 v195, v[4:7] offset:384
	v_add_f32_dpp v0, v91, v91 quad_perm:[1,0,3,2] row_mask:0xf bank_mask:0xf bound_ctrl:1
	s_add_u32 s76, s76, s31
	s_addc_u32 s77, s77, 0
	v_add_f32_dpp v0, v0, v0 quad_perm:[2,3,0,1] row_mask:0xf bank_mask:0xf bound_ctrl:1
	s_nop 1
	v_mov_b32_dpp v1, v0 row_half_mirror row_mask:0xf bank_mask:0xf bound_ctrl:1
	s_and_saveexec_b64 s[78:79], s[8:9]
	s_cbranch_execz .LBB0_525
	v_add_f32_e32 v2, v0, v1
	v_lshlrev_b64 v[0:1], 6, v[16:17]
	v_lshl_add_u64 v[0:1], s[76:77], 0, v[0:1]
	global_store_dword v[0:1], v2, off

; __device__ __forceinline__ int crow(int r, int hi) { return (r & 3) + 8 * (r >> 2) + 4 * hi; }
; __device__ void phase_scan(const Params& p, char* lds) {
;     ...
;         if (mat == 0) {
;           float cc[16];
; #pragma unroll
;           for (int r = 0; r < 16; ++r) cc[r] = -0.6065306597126334f * __builtin_amdgcn_rcpf(1.f + __expf(-(acc[r] + bias)));
; #pragma unroll
;           for (int g = 0; g < 4; ++g) { cc[4 * g + 1] += cc[4 * g]; cc[4 * g + 2] += cc[4 * g + 1]; cc[4 * g + 3] += cc[4 * g + 2]; }
;           float run = 0.f;
; #pragma unroll
;           for (int g = 0; g < 4; ++g) {
;             const float own = cc[4 * g + 3];
;             auto rr2 = __builtin_amdgcn_permlane32_swap(__float_as_uint(own), __float_as_uint(own), false, false);
;             const float both = __uint_as_float(rr2[0]) + __uint_as_float(rr2[1]), partner = both - own;
;             const float off = hi ? run + partner : run;
; #pragma unroll
;             for (int e = 0; e < 4; ++e) Pd[crow(4 * g + e, hi) * 64 + jh * 32 + r32] = __expf(off + cc[4 * g + e]);
;             run += both;
;           }
.LBB0_545:
	v_add_f32_e32 v10, v99, v15
	v_mul_f32_e32 v10, 0xbfb8aa3b, v10
	v_exp_f32_e32 v10, v10
	s_andn2_b64 vcc, exec, s[80:81]
	s_add_i32 s90, s88, 0
	v_add_f32_e32 v10, 1.0, v10
	v_rcp_f32_e32 v10, v10
	s_cbranch_vccnz .LBB0_547
	v_mul_f32_e64 v0, v0, s74
	v_mul_f32_e64 v1, v1, s75
	v_mul_f32_e64 v4, v4, s74
	v_mul_f32_e64 v5, v5, s75
	v_sub_f32_e32 v1, v0, v1
	v_fmamk_f32 v12, v86, 0xbf1b4598, v1
	v_sub_f32_e32 v5, v4, v5
	v_fmamk_f32 v13, v87, 0xbf1b4598, v12
	v_fmamk_f32 v86, v8, 0xbf1b4598, v5
	v_fmamk_f32 v87, v9, 0xbf1b4598, v86
	v_mov_b32_e32 v8, v13
	v_mov_b32_e32 v9, v13
	s_nop 1
	v_permlane32_swap_b32_e32 v8, v9
	v_add_f32_e32 v8, v8, v9
	v_sub_f32_e32 v9, v8, v13
	v_add_f32_e32 v9, 0, v9
	v_cndmask_b32_e64 v9, v9, 0, s[26:27]
	v_add_f32_e32 v0, v0, v9
	v_add_f32_e32 v1, v1, v9
	v_mul_f32_e32 v0, 0x3fb8aa3b, v0
	v_mul_f32_e32 v1, 0x3fb8aa3b, v1
	v_add_f32_e32 v12, v12, v9
	v_add_f32_e32 v9, v13, v9
	v_mul_f32_e64 v2, v2, s74
	v_mul_f32_e64 v3, v3, s75
	v_exp_f32_e32 v0, v0
	v_exp_f32_e32 v1, v1
	v_mul_f32_e32 v12, 0x3fb8aa3b, v12
	v_mul_f32_e32 v9, 0x3fb8aa3b, v9
	v_sub_f32_e32 v3, v2, v3
	v_exp_f32_e32 v12, v12
	v_exp_f32_e32 v9, v9
	v_fmamk_f32 v14, v88, 0xbf1b4598, v3
	v_fmamk_f32 v15, v89, 0xbf1b4598, v14
	v_lshl_add_u32 v13, v177, 2, s90
	ds_write2st64_b32 v13, v0, v1 offset1:1
	ds_write2st64_b32 v13, v12, v9 offset0:2 offset1:3
	v_add_f32_e32 v0, 0, v8
	v_mov_b32_e32 v1, v15
	v_mov_b32_e32 v8, v15
	s_nop 1
	v_permlane32_swap_b32_e32 v1, v8
	v_add_f32_e32 v8, v1, v8
	v_sub_f32_e32 v1, v8, v15
	v_add_f32_e32 v1, v0, v1
	v_cndmask_b32_e64 v1, v1, v0, s[26:27]
	v_add_f32_e32 v2, v2, v1
	v_add_f32_e32 v3, v3, v1
	v_add_f32_e32 v9, v14, v1
	v_add_f32_e32 v1, v15, v1
	v_mul_f32_e32 v9, 0x3fb8aa3b, v9
	v_mul_f32_e32 v1, 0x3fb8aa3b, v1
	v_exp_f32_e32 v12, v9
	v_exp_f32_e32 v14, v1
	v_mov_b32_e32 v1, v87
	v_mov_b32_e32 v9, v87
	s_nop 1
	v_permlane32_swap_b32_e32 v1, v9
	v_add_f32_e64 v0, v0, v8
	v_add_f32_e64 v1, v1, v9
	v_mul_f32_e32 v2, 0x3fb8aa3b, v2
	v_sub_f32_e32 v8, v1, v87
	v_add_f32_e32 v8, v0, v8
	v_mul_f32_e32 v3, 0x3fb8aa3b, v3
	v_cndmask_b32_e64 v8, v8, v0, s[26:27]
	v_mul_f32_e64 v6, v6, s74
	v_mul_f32_e64 v7, v7, s75
	v_exp_f32_e32 v2, v2
	v_exp_f32_e32 v3, v3
	v_add_f32_e32 v4, v4, v8
	v_add_f32_e32 v5, v5, v8
	v_sub_f32_e32 v7, v6, v7
	v_mul_f32_e32 v4, 0x3fb8aa3b, v4
	v_mul_f32_e32 v5, 0x3fb8aa3b, v5
	v_add_f32_e32 v9, v86, v8
	v_add_f32_e32 v8, v87, v8
	v_fmamk_f32 v11, v11, 0xbf1b4598, v7
	v_exp_f32_e32 v4, v4
	v_exp_f32_e32 v5, v5
	v_mul_f32_e32 v9, 0x3fb8aa3b, v9
	v_mul_f32_e32 v8, 0x3fb8aa3b, v8
	v_fmamk_f32 v10, v10, 0xbf1b4598, v11
	v_exp_f32_e32 v9, v9
	v_exp_f32_e32 v8, v8
	ds_write2st64_b32 v13, v2, v3 offset0:8 offset1:9
	ds_write2st64_b32 v13, v12, v14 offset0:10 offset1:11
	ds_write2st64_b32 v13, v4, v5 offset0:16 offset1:17
	ds_write2st64_b32 v13, v9, v8 offset0:18 offset1:19
	v_mov_b32_e32 v3, v10
	v_mov_b32_e32 v5, v10
	s_nop 1
	v_permlane32_swap_b32_e32 v3, v5
	s_nop 0
	v_mov_b32_e32 v4, v1
	v_add_f32_e64 v0, v0, v4
	v_add_f32_e64 v1, v3, v5
	s_mov_b32 s80, s90
	v_sub_f32_e32 v1, v1, v10
	v_add_f32_e32 v1, v0, v1
	v_cndmask_b32_e64 v0, v1, v0, s[26:27]
	v_add_f32_e32 v1, v6, v0
	v_add_f32_e32 v2, v7, v0
	v_add_f32_e32 v3, v11, v0
	v_add_f32_e32 v0, v10, v0
	v_mul_f32_e32 v1, 0x3fb8aa3b, v1
	v_mul_f32_e32 v2, 0x3fb8aa3b, v2
	v_mul_f32_e32 v0, 0x3fb8aa3b, v0
	v_exp_f32_e32 v1, v1
	v_exp_f32_e32 v2, v2
	v_mul_f32_e32 v3, 0x3fb8aa3b, v3
	v_exp_f32_e32 v10, v0
	v_exp_f32_e32 v3, v3
	ds_write2st64_b32 v13, v1, v2 offset0:24 offset1:25
	ds_write_b32 v13, v3 offset:6656
	s_branch .LBB0_548

; __device__ void phase_scan(const Params& p, char* lds) {
;     ...
;         const float inv = rsqrtf(fmaxf(ss, 1e-24f));
; #pragma unroll
;         for (int e = 0; e < 8; ++e) kk[e] *= inv;
;       };
;       auto stageB = [&](int c) {
;         char* buf = lds + (c & 1) * SC_BUF;
;         const f32x4 i0 = *(const f32x4*)(IC + pstep * 64 + j0), i1 = *(const f32x4*)(IC + pstep * 64 + j0 + 4);
;         const float ic[8] = {i0[0], i0[1], i0[2], i0[3], i1[0], i1[1], i1[2], i1[3]};
;         const float* Pt = (const float*)(buf + SC_P) + pstep * 64 + j0;
;         const f32x4 pt0 = *(const f32x4*)(Pt), pt1 = *(const f32x4*)(Pt + 4);
;         f32x4 pm0 = {1.f, 1.f, 1.f, 1.f}, pm1 = pm0;
;         if (pstep > 0) { pm0 = *(const f32x4*)(Pt - 64); pm1 = *(const f32x4*)(Pt - 60); }
;         const float pt[8] = {pt0[0], pt0[1], pt0[2], pt0[3], pt1[0], pt1[1], pt1[2], pt1[3]};
;         const float pm[8] = {pm0[0], pm0[1], pm0[2], pm0[3], pm1[0], pm1[1], pm1[2], pm1[3]};
;         const u32x4 an = {cvtpk(-kk[0] * pm[0], -kk[1] * pm[1]), cvtpk(-kk[2] * pm[2], -kk[3] * pm[3]), cvtpk(-kk[4] * pm[4], -kk[5] * pm[5]), cvtpk(-kk[6] * pm[6], -kk[7] * pm[7])};
;         const u32x4 rn = {cvtpk(rr[0] * pt[0], rr[1] * pt[1]), cvtpk(rr[2] * pt[2], rr[3] * pt[3]), cvtpk(rr[4] * pt[4], rr[5] * pt[5]), cvtpk(rr[6] * pt[6], rr[7] * pt[7])};
;         bf16_t* ARa = (bf16_t*)(buf + SC_ARA) + (pblk * 4 + psb) * 64; bf16_t* ARr = (bf16_t*)(buf + SC_ARR) + (pblk * 4 + psb) * 64;
;         { u32x2 lo = {an[0], an[1]}, hi2 = {an[2], an[3]}; *(u32x2*)(ARa + apos0) = lo; *(u32x2*)(ARa + apos1) = hi2; }
;         { u32x2 lo = {rn[0], rn[1]}, hi2 = {rn[2], rn[3]}; *(u32x2*)(ARr + apos0) = lo; *(u32x2*)(ARr + apos1) = hi2; }
;         *(u32x4*)(SCR + (pstep * 4 + 0) * 64 + j0) = an; *(u32x4*)(SCR + (pstep * 4 + 1) * 64 + j0) = rn;
;         float bs = 0.f;
;         unsigned bq[8], kq[8];
;         unsigned* BK = (unsigned*)(buf + SC_BK) + (pblk * 64 + j0) * 4 + psb;
; #pragma unroll
;         for (int e = 0; e < 8; ++e) {
;           const float kd = kr[e] * (1.f + (ic[e] - 1.f) * kac[e]);
;           const float ip = __builtin_amdgcn_rcpf(pt[e]);
;           const unsigned pr2 = cvtpk(kk[e] * ic[e] * ip, kd * ip);
;           BK[e * 4] = pr2;
;           bq[e] = pr2 & 0xffffu; kq[e] = pr2 >> 16;
;           bs += rr[e] * kd * rkc[e];
;         }
.LBB0_552:
	s_or_b64 exec, exec, s[80:81]
	v_add_f32_e32 v123, v123, v124
	v_max_f32_e32 v123, 0x179abe15, v123
	v_rsq_f32_e32 v124, v123
	v_lshlrev_b32_e32 v126, 16, v75
	v_and_b32_e32 v127, 0xffff0000, v75
	v_lshlrev_b32_e32 v128, 16, v76
	v_mul_f32_e64 v112, v112, v124
	v_mul_f32_e64 v113, v113, v124
	v_mul_f32_e64 v114, v114, v124
	v_mul_f32_e64 v115, v115, v124
	v_mul_f32_e64 v116, v116, v124
	v_mul_f32_e64 v117, v117, v124
	v_mul_f32_e64 v118, v118, v124
	v_mul_f32_e64 v119, v119, v124
	v_lshlrev_b32_e32 v124, 16, v74
	v_and_b32_e32 v125, 0xffff0000, v74
	v_and_b32_e32 v129, 0xffff0000, v76
	v_lshlrev_b32_e32 v130, 16, v77
	v_and_b32_e32 v131, 0xffff0000, v77
	s_waitcnt lgkmcnt(1)
	v_mul_f32_e64 v74, v94, -v112
	v_mul_f32_e64 v75, v95, -v113
	v_mul_f32_e64 v76, v96, -v114
	v_mul_f32_e64 v77, v97, -v115
	v_cvt_pk_bf16_f32 v74, v74, v75
	v_cvt_pk_bf16_f32 v75, v76, v77
	s_waitcnt lgkmcnt(0)
	v_mul_f32_e64 v76, v90, -v116
	v_mul_f32_e64 v77, v91, -v117
	v_mul_f32_e64 v90, v92, -v118
	v_mul_f32_e64 v91, v93, -v119
	v_cvt_pk_bf16_f32 v76, v76, v77
	v_cvt_pk_bf16_f32 v77, v90, v91
	v_mul_f32_e64 v90, v124, v86
	v_mul_f32_e64 v91, v125, v87
	v_mul_f32_e64 v92, v126, v88
	v_mul_f32_e64 v93, v127, v89
	v_cvt_pk_bf16_f32 v90, v90, v91
	v_cvt_pk_bf16_f32 v91, v92, v93
	v_mul_f32_e64 v92, v128, v78
	v_mul_f32_e64 v93, v129, v79
	v_mul_f32_e64 v94, v130, v80
	v_mul_f32_e64 v95, v131, v81
	v_cvt_pk_bf16_f32 v92, v92, v93
	v_cvt_pk_bf16_f32 v93, v94, v95
	v_add3_u32 v94, s90, v192, v193
	v_add_u32_e32 v95, 0x2000, v94
	v_add_u32_e32 v94, 0x3000, v94
	ds_write2_b64 v95, v[74:75], v[76:77] offset1:2
	ds_write2_b64 v94, v[90:91], v[92:93] offset1:2
	ds_write_b128 v195, v[74:77]
	ds_write_b128 v195, v[90:93] offset:128
	v_rcp_f32_e32 v76, v86
	v_add_f32_e32 v74, -1.0, v82
	v_fma_f32 v75, v22, v74, 1.0
	s_nop 0
	s_nop 0
	s_nop 0
	v_mul_f32_e64 v74, v112, v82
	v_mul_f32_e64 v75, v110, v75
	v_mov_b32_e32 v110, v113
	v_mul_f32_e64 v77, v75, v76
	v_mul_f32_e64 v76, v74, v76
	v_mul_f32_e32 v74, v124, v75
	v_cvt_pk_bf16_f32 v82, v76, v77
	v_rcp_f32_e32 v76, v87
	v_fma_f32 v91, v30, v74, 0
	v_add_f32_e32 v74, -1.0, v83
	v_fma_f32 v75, v23, v74, 1.0
	s_nop 0
	v_mul_f32_e64 v74, v110, v83
	v_mul_f32_e64 v75, v111, v75
	v_add3_u32 v92, s90, v196, v197
	v_mul_f32_e64 v77, v75, v76
	v_mul_f32_e64 v76, v74, v76
	v_mul_f32_e32 v74, v125, v75
	v_cvt_pk_bf16_f32 v87, v76, v77
	v_rcp_f32_e32 v76, v88
	v_add_u32_e32 v92, 0x4000, v92
	v_fmac_f32_e32 v91, v31, v74
	v_add_f32_e32 v74, -1.0, v84
	v_and_b32_e32 v86, 0xffff, v82
	v_lshrrev_b32_e32 v90, 16, v82
	ds_write2_b32 v92, v82, v87 offset1:4
	v_fma_f32 v75, v24, v74, 1.0
	s_nop 0
	s_nop 0
	s_nop 0
	v_mul_f32_e64 v74, v114, v84
	v_mul_f32_e64 v75, v108, v75
	v_mov_b32_e32 v108, v115
	v_mul_f32_e64 v77, v75, v76
	v_mul_f32_e64 v76, v74, v76
	v_mul_f32_e32 v74, v126, v75
	v_cvt_pk_bf16_f32 v82, v76, v77
	v_rcp_f32_e32 v76, v89
	v_fmac_f32_e32 v91, v32, v74
	v_add_f32_e32 v74, -1.0, v85
	v_fma_f32 v75, v25, v74, 1.0
	s_nop 0
	v_mul_f32_e64 v74, v108, v85
	v_mul_f32_e64 v75, v109, v75
	v_and_b32_e32 v84, 0xffff, v82
	v_mul_f32_e64 v77, v75, v76
	v_mul_f32_e64 v76, v74, v76
	v_mul_f32_e32 v74, v127, v75
	v_cvt_pk_bf16_f32 v85, v76, v77
	v_fmac_f32_e32 v91, v33, v74
	v_add_f32_e32 v74, -1.0, v12
	v_lshrrev_b32_e32 v88, 16, v82
	ds_write2_b32 v92, v82, v85 offset0:8 offset1:12
	v_fma_f32 v75, v18, v74, 1.0
	v_rcp_f32_e32 v76, v78
	s_nop 0
	v_mov_b32_e32 v83, v106
	s_nop 0
	v_mul_f32_e64 v74, v116, v12
	v_mul_f32_e64 v75, v83, v75
	v_mov_b32_e32 v106, v117
	v_mul_f32_e32 v12, v128, v75
	v_fmac_f32_e32 v91, v26, v12
	v_add_f32_e32 v12, -1.0, v13
	v_mul_f32_e64 v77, v75, v76
	v_mul_f32_e64 v76, v74, v76
	v_fma_f32 v75, v19, v12, 1.0
	v_rcp_f32_e32 v12, v79
	s_nop 0
	v_mul_f32_e64 v74, v106, v13
	v_mul_f32_e64 v75, v107, v75
	v_cvt_pk_bf16_f32 v76, v76, v77
	v_mul_f32_e64 v13, v75, v12
	v_mul_f32_e64 v12, v74, v12
	v_rcp_f32_e32 v74, v80
	v_cvt_pk_bf16_f32 v79, v12, v13
	v_mul_f32_e32 v12, v129, v75
	v_fmac_f32_e32 v91, v27, v12
	v_add_f32_e32 v12, -1.0, v14
	v_and_b32_e32 v78, 0xffff, v76
	v_lshrrev_b32_e32 v82, 16, v76
	ds_write2_b32 v92, v76, v79 offset0:16 offset1:20
	v_fma_f32 v13, v20, v12, 1.0
	s_nop 0
	s_nop 0
	s_nop 0
	v_mul_f32_e64 v12, v118, v14
	v_mul_f32_e64 v13, v104, v13
	v_rcp_f32_e32 v14, v81
	v_mul_f32_e64 v75, v13, v74
	v_mul_f32_e64 v74, v12, v74
	v_mul_f32_e32 v12, v130, v13
	v_fmac_f32_e32 v91, v28, v12
	v_add_f32_e32 v12, -1.0, v15
	v_fma_f32 v13, v21, v12, 1.0
	v_mov_b32_e32 v104, v119
	s_nop 0
	v_mul_f32_e64 v12, v104, v15
	v_mul_f32_e64 v13, v105, v13
	v_cvt_pk_bf16_f32 v74, v74, v75
	v_mul_f32_e64 v15, v13, v14
	v_mul_f32_e64 v14, v12, v14
	v_and_b32_e32 v75, 0xffff, v74
	v_cvt_pk_bf16_f32 v80, v14, v15
	v_mul_f32_e32 v12, v131, v13
	v_lshrrev_b32_e32 v77, 16, v74
	v_fmac_f32_e32 v91, v29, v12
	v_lshl_or_b32 v12, v87, 16, v86
	v_lshl_or_b32 v13, v85, 16, v84
	v_lshl_or_b32 v14, v79, 16, v78
	v_lshl_or_b32 v15, v80, 16, v75
	ds_write2_b32 v92, v74, v80 offset0:24 offset1:28
	v_and_or_b32 v74, v87, s1, v90
	v_and_or_b32 v75, v85, s1, v88
	v_and_or_b32 v76, v79, s1, v82
	v_and_or_b32 v77, v80, s1, v77
	ds_write_b128 v195, v[12:15] offset:256
	ds_write_b128 v195, v[74:77] offset:384
	v_add_f32_dpp v12, v91, v91 quad_perm:[1,0,3,2] row_mask:0xf bank_mask:0xf bound_ctrl:1
	s_nop 1
	v_add_f32_dpp v12, v12, v12 quad_perm:[2,3,0,1] row_mask:0xf bank_mask:0xf bound_ctrl:1
	s_nop 1
	v_mov_b32_dpp v13, v12 row_half_mirror row_mask:0xf bank_mask:0xf bound_ctrl:1
	s_and_saveexec_b64 s[80:81], s[8:9]
	s_cbranch_execz .LBB0_554
	v_add_f32_e32 v14, v12, v13
	v_add_u32_e32 v12, 64, v122
	v_cmp_gt_i32_e32 vcc, s92, v12
	v_add_u32_e32 v13, 0xffffff40, v122
	s_movk_i32 s88, 0xffc0
	v_cndmask_b32_e32 v15, v220, v221, vcc
	v_cndmask_b32_e32 v12, v13, v12, vcc
	v_mov_b32_e32 v13, s34
	v_mov_b32_e32 v74, s35
	v_add3_u32 v15, v15, v120, s88
	v_cndmask_b32_e32 v13, v13, v74, vcc
	v_cndmask_b32_e64 v12, v15, v12, s[22:23]
	v_add_u32_e32 v12, v12, v13
	v_ashrrev_i32_e32 v13, 31, v12
	v_lshlrev_b64 v[12:13], 6, v[12:13]
	v_lshl_add_u64 v[12:13], s[76:77], 0, v[12:13]
	global_store_dword v[12:13], v14, off
